# v51 + P0 rg-gate-weight conversion: nine source loads batched per thread, pointers via scalar loads (was 9 x two dependent global loads)
# baseline (speedup 1.0000x reference)
.LBB0_78:
	s_mov_b64 s[2:3], 0x120000
	v_cmp_gt_u64_e32 vcc, s[2:3], v[172:173]
	s_and_saveexec_b64 s[2:3], vcc
	s_mov_b32 s34, 0xc200000
	s_cbranch_execz .LBB0_83
	v_readlane_b32 s6, v254, 51
	s_add_u32 s6, s64, s6
	v_readlane_b32 s7, v254, 52
	s_addc_u32 s7, s65, s7
	v_mov_b64_e32 v[4:5], v[172:173]
	v_lshl_add_u64 v[2:3], v[170:171], 1, s[6:7]
	s_mov_b64 s[6:7], 0
	s_cmp_eq_u32 s56, 0x100
	s_cbranch_scc0 .LBB0_81
	v_readfirstlane_b32 s100, v217
	v_readfirstlane_b32 s101, v230
	v_readlane_b32 s8, v254, 53
	v_readlane_b32 s9, v254, 54
	s_nop 3
	s_load_dwordx2 s[10:11], s[0:1], s100
	s_load_dwordx2 s[98:99], s[0:1], s101
	s_mov_b32 s6, 0xaaaaaaab
	s_mov_b32 s7, 0x38e38e39
	v_and_b32_e32 v4, 63, v208
	s_waitcnt lgkmcnt(0)
	v_readfirstlane_b32 s101, v172
	s_mul_hi_u32 s100, s101, s7
	s_lshr_b32 s100, s100, 11
	s_bitcmp1_b32 s100, 4
	s_cselect_b32 s42, s10, s98
	s_cselect_b32 s43, s11, s99
	v_add_u32_e32 v5, s101, v4
	s_mul_i32 s101, s100, 0x60
	v_mul_hi_u32 v6, v5, s6
	v_lshrrev_b32_e32 v6, 6, v6
	v_mul_u32_u24_e32 v7, 0x60, v6
	v_sub_u32_e32 v7, v5, v7
	v_subrev_u32_e32 v8, s101, v6
	s_lshr_b32 s101, s100, 5
	s_and_b32 s100, s100, 15
	s_lshl_b32 s101, s101, 4
	s_or_b32 s100, s100, s101
	s_mul_i32 s100, s100, 0x58
	v_add_u32_e32 v9, s100, v7
	v_mul_u32_u24_e32 v9, 0x58, v9
	v_add_lshl_u32 v9, v9, v8, 2
	v_cmp_gt_u32_e32 vcc, 0x58, v7
	s_mov_b64 s[100:101], vcc
	v_cmp_gt_u32_e32 vcc, 0x58, v8
	s_and_b64 vcc, vcc, s[100:101]
	s_nop 1
	v_cndmask_b32_e32 v9, 0, v9, vcc
	v_cndmask_b32_e64 v20, 0, -1, vcc
	global_load_dword v30, v9, s[42:43]
	v_readfirstlane_b32 s101, v172
	s_add_u32 s101, s101, 0x20000
	s_mul_hi_u32 s100, s101, s7
	s_lshr_b32 s100, s100, 11
	s_bitcmp1_b32 s100, 4
	s_cselect_b32 s42, s10, s98
	s_cselect_b32 s43, s11, s99
	v_add_u32_e32 v5, s101, v4
	s_mul_i32 s101, s100, 0x60
	v_mul_hi_u32 v6, v5, s6
	v_lshrrev_b32_e32 v6, 6, v6
	v_mul_u32_u24_e32 v7, 0x60, v6
	v_sub_u32_e32 v7, v5, v7
	v_subrev_u32_e32 v8, s101, v6
	s_lshr_b32 s101, s100, 5
	s_and_b32 s100, s100, 15
	s_lshl_b32 s101, s101, 4
	s_or_b32 s100, s100, s101
	s_mul_i32 s100, s100, 0x58
	v_add_u32_e32 v9, s100, v7
	v_mul_u32_u24_e32 v9, 0x58, v9
	v_add_lshl_u32 v9, v9, v8, 2
	v_cmp_gt_u32_e32 vcc, 0x58, v7
	s_mov_b64 s[100:101], vcc
	v_cmp_gt_u32_e32 vcc, 0x58, v8
	s_and_b64 vcc, vcc, s[100:101]
	s_nop 1
	v_cndmask_b32_e32 v9, 0, v9, vcc
	v_cndmask_b32_e64 v21, 0, -1, vcc
	global_load_dword v31, v9, s[42:43]
	v_readfirstlane_b32 s101, v172
	s_add_u32 s101, s101, 0x40000
	s_mul_hi_u32 s100, s101, s7
	s_lshr_b32 s100, s100, 11
	s_bitcmp1_b32 s100, 4
	s_cselect_b32 s42, s10, s98
	s_cselect_b32 s43, s11, s99
	v_add_u32_e32 v5, s101, v4
	s_mul_i32 s101, s100, 0x60
	v_mul_hi_u32 v6, v5, s6
	v_lshrrev_b32_e32 v6, 6, v6
	v_mul_u32_u24_e32 v7, 0x60, v6
	v_sub_u32_e32 v7, v5, v7
	v_subrev_u32_e32 v8, s101, v6
	s_lshr_b32 s101, s100, 5
	s_and_b32 s100, s100, 15
	s_lshl_b32 s101, s101, 4
	s_or_b32 s100, s100, s101
	s_mul_i32 s100, s100, 0x58
	v_add_u32_e32 v9, s100, v7
	v_mul_u32_u24_e32 v9, 0x58, v9
	v_add_lshl_u32 v9, v9, v8, 2
	v_cmp_gt_u32_e32 vcc, 0x58, v7
	s_mov_b64 s[100:101], vcc
	v_cmp_gt_u32_e32 vcc, 0x58, v8
	s_and_b64 vcc, vcc, s[100:101]
	s_nop 1
	v_cndmask_b32_e32 v9, 0, v9, vcc
	v_cndmask_b32_e64 v22, 0, -1, vcc
	global_load_dword v32, v9, s[42:43]
	v_readfirstlane_b32 s101, v172
	s_add_u32 s101, s101, 0x60000
	s_mul_hi_u32 s100, s101, s7
	s_lshr_b32 s100, s100, 11
	s_bitcmp1_b32 s100, 4
	s_cselect_b32 s42, s10, s98
	s_cselect_b32 s43, s11, s99
	v_add_u32_e32 v5, s101, v4
	s_mul_i32 s101, s100, 0x60
	v_mul_hi_u32 v6, v5, s6
	v_lshrrev_b32_e32 v6, 6, v6
	v_mul_u32_u24_e32 v7, 0x60, v6
	v_sub_u32_e32 v7, v5, v7
	v_subrev_u32_e32 v8, s101, v6
	s_lshr_b32 s101, s100, 5
	s_and_b32 s100, s100, 15
	s_lshl_b32 s101, s101, 4
	s_or_b32 s100, s100, s101
	s_mul_i32 s100, s100, 0x58
	v_add_u32_e32 v9, s100, v7
	v_mul_u32_u24_e32 v9, 0x58, v9
	v_add_lshl_u32 v9, v9, v8, 2
	v_cmp_gt_u32_e32 vcc, 0x58, v7
	s_mov_b64 s[100:101], vcc
	v_cmp_gt_u32_e32 vcc, 0x58, v8
	s_and_b64 vcc, vcc, s[100:101]
	s_nop 1
	v_cndmask_b32_e32 v9, 0, v9, vcc
	v_cndmask_b32_e64 v23, 0, -1, vcc
	global_load_dword v33, v9, s[42:43]
	v_readfirstlane_b32 s101, v172
	s_add_u32 s101, s101, 0x80000
	s_mul_hi_u32 s100, s101, s7
	s_lshr_b32 s100, s100, 11
	s_bitcmp1_b32 s100, 4
	s_cselect_b32 s42, s10, s98
	s_cselect_b32 s43, s11, s99
	v_add_u32_e32 v5, s101, v4
	s_mul_i32 s101, s100, 0x60
	v_mul_hi_u32 v6, v5, s6
	v_lshrrev_b32_e32 v6, 6, v6
	v_mul_u32_u24_e32 v7, 0x60, v6
	v_sub_u32_e32 v7, v5, v7
	v_subrev_u32_e32 v8, s101, v6
	s_lshr_b32 s101, s100, 5
	s_and_b32 s100, s100, 15
	s_lshl_b32 s101, s101, 4
	s_or_b32 s100, s100, s101
	s_mul_i32 s100, s100, 0x58
	v_add_u32_e32 v9, s100, v7
	v_mul_u32_u24_e32 v9, 0x58, v9
	v_add_lshl_u32 v9, v9, v8, 2
	v_cmp_gt_u32_e32 vcc, 0x58, v7
	s_mov_b64 s[100:101], vcc
	v_cmp_gt_u32_e32 vcc, 0x58, v8
	s_and_b64 vcc, vcc, s[100:101]
	s_nop 1
	v_cndmask_b32_e32 v9, 0, v9, vcc
	v_cndmask_b32_e64 v24, 0, -1, vcc
	global_load_dword v34, v9, s[42:43]
	v_readfirstlane_b32 s101, v172
	s_add_u32 s101, s101, 0xa0000
	s_mul_hi_u32 s100, s101, s7
	s_lshr_b32 s100, s100, 11
	s_bitcmp1_b32 s100, 4
	s_cselect_b32 s42, s10, s98
	s_cselect_b32 s43, s11, s99
	v_add_u32_e32 v5, s101, v4
	s_mul_i32 s101, s100, 0x60
	v_mul_hi_u32 v6, v5, s6
	v_lshrrev_b32_e32 v6, 6, v6
	v_mul_u32_u24_e32 v7, 0x60, v6
	v_sub_u32_e32 v7, v5, v7
	v_subrev_u32_e32 v8, s101, v6
	s_lshr_b32 s101, s100, 5
	s_and_b32 s100, s100, 15
	s_lshl_b32 s101, s101, 4
	s_or_b32 s100, s100, s101
	s_mul_i32 s100, s100, 0x58
	v_add_u32_e32 v9, s100, v7
	v_mul_u32_u24_e32 v9, 0x58, v9
	v_add_lshl_u32 v9, v9, v8, 2
	v_cmp_gt_u32_e32 vcc, 0x58, v7
	s_mov_b64 s[100:101], vcc
	v_cmp_gt_u32_e32 vcc, 0x58, v8
	s_and_b64 vcc, vcc, s[100:101]
	s_nop 1
	v_cndmask_b32_e32 v9, 0, v9, vcc
	v_cndmask_b32_e64 v25, 0, -1, vcc
	global_load_dword v35, v9, s[42:43]
	v_readfirstlane_b32 s101, v172
	s_add_u32 s101, s101, 0xc0000
	s_mul_hi_u32 s100, s101, s7
	s_lshr_b32 s100, s100, 11
	s_bitcmp1_b32 s100, 4
	s_cselect_b32 s42, s10, s98
	s_cselect_b32 s43, s11, s99
	v_add_u32_e32 v5, s101, v4
	s_mul_i32 s101, s100, 0x60
	v_mul_hi_u32 v6, v5, s6
	v_lshrrev_b32_e32 v6, 6, v6
	v_mul_u32_u24_e32 v7, 0x60, v6
	v_sub_u32_e32 v7, v5, v7
	v_subrev_u32_e32 v8, s101, v6
	s_lshr_b32 s101, s100, 5
	s_and_b32 s100, s100, 15
	s_lshl_b32 s101, s101, 4
	s_or_b32 s100, s100, s101
	s_mul_i32 s100, s100, 0x58
	v_add_u32_e32 v9, s100, v7
	v_mul_u32_u24_e32 v9, 0x58, v9
	v_add_lshl_u32 v9, v9, v8, 2
	v_cmp_gt_u32_e32 vcc, 0x58, v7
	s_mov_b64 s[100:101], vcc
	v_cmp_gt_u32_e32 vcc, 0x58, v8
	s_and_b64 vcc, vcc, s[100:101]
	s_nop 1
	v_cndmask_b32_e32 v9, 0, v9, vcc
	v_cndmask_b32_e64 v26, 0, -1, vcc
	global_load_dword v36, v9, s[42:43]
	v_readfirstlane_b32 s101, v172
	s_add_u32 s101, s101, 0xe0000
	s_mul_hi_u32 s100, s101, s7
	s_lshr_b32 s100, s100, 11
	s_bitcmp1_b32 s100, 4
	s_cselect_b32 s42, s10, s98
	s_cselect_b32 s43, s11, s99
	v_add_u32_e32 v5, s101, v4
	s_mul_i32 s101, s100, 0x60
	v_mul_hi_u32 v6, v5, s6
	v_lshrrev_b32_e32 v6, 6, v6
	v_mul_u32_u24_e32 v7, 0x60, v6
	v_sub_u32_e32 v7, v5, v7
	v_subrev_u32_e32 v8, s101, v6
	s_lshr_b32 s101, s100, 5
	s_and_b32 s100, s100, 15
	s_lshl_b32 s101, s101, 4
	s_or_b32 s100, s100, s101
	s_mul_i32 s100, s100, 0x58
	v_add_u32_e32 v9, s100, v7
	v_mul_u32_u24_e32 v9, 0x58, v9
	v_add_lshl_u32 v9, v9, v8, 2
	v_cmp_gt_u32_e32 vcc, 0x58, v7
	s_mov_b64 s[100:101], vcc
	v_cmp_gt_u32_e32 vcc, 0x58, v8
	s_and_b64 vcc, vcc, s[100:101]
	s_nop 1
	v_cndmask_b32_e32 v9, 0, v9, vcc
	v_cndmask_b32_e64 v27, 0, -1, vcc
	global_load_dword v37, v9, s[42:43]
	v_readfirstlane_b32 s101, v172
	s_add_u32 s101, s101, 0x100000
	s_mul_hi_u32 s100, s101, s7
	s_lshr_b32 s100, s100, 11
	s_bitcmp1_b32 s100, 4
	s_cselect_b32 s42, s10, s98
	s_cselect_b32 s43, s11, s99
	v_add_u32_e32 v5, s101, v4
	s_mul_i32 s101, s100, 0x60
	v_mul_hi_u32 v6, v5, s6
	v_lshrrev_b32_e32 v6, 6, v6
	v_mul_u32_u24_e32 v7, 0x60, v6
	v_sub_u32_e32 v7, v5, v7
	v_subrev_u32_e32 v8, s101, v6
	s_lshr_b32 s101, s100, 5
	s_and_b32 s100, s100, 15
	s_lshl_b32 s101, s101, 4
	s_or_b32 s100, s100, s101
	s_mul_i32 s100, s100, 0x58
	v_add_u32_e32 v9, s100, v7
	v_mul_u32_u24_e32 v9, 0x58, v9
	v_add_lshl_u32 v9, v9, v8, 2
	v_cmp_gt_u32_e32 vcc, 0x58, v7
	s_mov_b64 s[100:101], vcc
	v_cmp_gt_u32_e32 vcc, 0x58, v8
	s_and_b64 vcc, vcc, s[100:101]
	s_nop 1
	v_cndmask_b32_e32 v9, 0, v9, vcc
	v_cndmask_b32_e64 v28, 0, -1, vcc
	global_load_dword v38, v9, s[42:43]
	s_waitcnt vmcnt(8)
	v_and_b32_e32 v30, v30, v20
	v_bfe_u32 v5, v30, 16, 1
	v_add3_u32 v5, v30, v5, s90
	global_store_short_d16_hi v[2:3], v5, off
	v_lshl_add_u64 v[2:3], v[2:3], 0, s[8:9]
	s_waitcnt vmcnt(8)
	v_and_b32_e32 v31, v31, v21
	v_bfe_u32 v5, v31, 16, 1
	v_add3_u32 v5, v31, v5, s90
	global_store_short_d16_hi v[2:3], v5, off
	v_lshl_add_u64 v[2:3], v[2:3], 0, s[8:9]
	s_waitcnt vmcnt(8)
	v_and_b32_e32 v32, v32, v22
	v_bfe_u32 v5, v32, 16, 1
	v_add3_u32 v5, v32, v5, s90
	global_store_short_d16_hi v[2:3], v5, off
	v_lshl_add_u64 v[2:3], v[2:3], 0, s[8:9]
	s_waitcnt vmcnt(8)
	v_and_b32_e32 v33, v33, v23
	v_bfe_u32 v5, v33, 16, 1
	v_add3_u32 v5, v33, v5, s90
	global_store_short_d16_hi v[2:3], v5, off
	v_lshl_add_u64 v[2:3], v[2:3], 0, s[8:9]
	s_waitcnt vmcnt(8)
	v_and_b32_e32 v34, v34, v24
	v_bfe_u32 v5, v34, 16, 1
	v_add3_u32 v5, v34, v5, s90
	global_store_short_d16_hi v[2:3], v5, off
	v_lshl_add_u64 v[2:3], v[2:3], 0, s[8:9]
	s_waitcnt vmcnt(8)
	v_and_b32_e32 v35, v35, v25
	v_bfe_u32 v5, v35, 16, 1
	v_add3_u32 v5, v35, v5, s90
	global_store_short_d16_hi v[2:3], v5, off
	v_lshl_add_u64 v[2:3], v[2:3], 0, s[8:9]
	s_waitcnt vmcnt(8)
	v_and_b32_e32 v36, v36, v26
	v_bfe_u32 v5, v36, 16, 1
	v_add3_u32 v5, v36, v5, s90
	global_store_short_d16_hi v[2:3], v5, off
	v_lshl_add_u64 v[2:3], v[2:3], 0, s[8:9]
	s_waitcnt vmcnt(8)
	v_and_b32_e32 v37, v37, v27
	v_bfe_u32 v5, v37, 16, 1
	v_add3_u32 v5, v37, v5, s90
	global_store_short_d16_hi v[2:3], v5, off
	v_lshl_add_u64 v[2:3], v[2:3], 0, s[8:9]
	s_waitcnt vmcnt(8)
	v_and_b32_e32 v38, v38, v28
	v_bfe_u32 v5, v38, 16, 1
	v_add3_u32 v5, v38, v5, s90
	global_store_short_d16_hi v[2:3], v5, off
	s_branch .LBB0_83
